# v89 plus up-projection epilogue: lanes transposed with ds_bpermute so each quad stores 64 contiguous bytes, SGPR-base + 32-bit offset store addressing (v_mad_u32_u24 instead of 64-bit mad)
# baseline (speedup 1.0000x reference)
.Lepib_up_exit:
.Lpeelx4:
	v_mul_f32_e32 v144, 0xbfb8aa3b, v127
	v_mul_f32_e32 v141, 0xbfb8aa3b, v126
	v_exp_f32_e32 v145, v144
	v_mul_f32_e32 v144, 0xbfb8aa3b, v128
	v_exp_f32_e32 v141, v141
	v_exp_f32_e32 v146, v144
	v_mul_f32_e32 v144, 0xbfb8aa3b, v129
	v_exp_f32_e32 v147, v144
	v_mul_f32_e32 v144, 0xbfb8aa3b, v122
	v_exp_f32_e32 v148, v144
	v_mul_f32_e32 v144, 0xbfb8aa3b, v123
	v_exp_f32_e32 v149, v144
	v_mul_f32_e32 v144, 0xbfb8aa3b, v124
	v_exp_f32_e32 v150, v144
	v_mul_f32_e32 v144, 0xbfb8aa3b, v125
	v_add_f32_e32 v141, 1.0, v141
	v_exp_f32_e32 v151, v144
	v_rcp_f32_e32 v144, v141
	v_add_f32_e32 v141, 1.0, v145
	v_rcp_f32_e32 v145, v141
	v_add_f32_e32 v141, 1.0, v146
	v_rcp_f32_e32 v146, v141
	v_add_f32_e32 v141, 1.0, v147
	v_rcp_f32_e32 v147, v141
	v_add_f32_e32 v141, 1.0, v148
	v_rcp_f32_e32 v148, v141
	v_add_f32_e32 v141, 1.0, v149
	v_rcp_f32_e32 v149, v141
	v_add_f32_e32 v141, 1.0, v150
	v_rcp_f32_e32 v150, v141
	v_add_f32_e32 v141, 1.0, v151
	v_pk_mul_f32 v[126:127], v[126:127], v[144:145]
	v_rcp_f32_e32 v151, v141
	v_pk_mul_f32 v[118:119], v[126:127], v[118:119]
	v_pk_mul_f32 v[126:127], v[128:129], v[146:147]
	v_cvt_pk_f16_f32 v118, v118, v119
	v_pk_mul_f32 v[120:121], v[126:127], v[120:121]
	v_bfe_u32 v152, v220, 2, 4
	v_and_b32_e32 v155, 3, v220
	v_and_b32_e32 v153, 0xfffffff0, v136
	v_or_b32_e32 v153, v153, v152
	v_and_b32_e32 v154, 0xffffffe7, v138
	v_lshl_or_b32 v154, v155, 3, v154
	v_lshl_or_b32 v152, v155, 4, v152
	v_lshlrev_b32_e32 v152, 2, v152
	v_lshl_or_b32 v142, s36, 7, v154
	v_cvt_pk_f16_f32 v119, v120, v121
	v_pk_mul_f32 v[120:121], v[122:123], v[148:149]
	v_lshl_add_u32 v140, s8, 8, v153
	v_pk_mul_f32 v[114:115], v[120:121], v[114:115]
	v_ashrrev_i32_e32 v143, 31, v142
	v_cvt_pk_f16_f32 v120, v114, v115
	v_pk_mul_f32 v[114:115], v[124:125], v[150:151]
	s_movk_i32 s3, 0x1600
	v_pk_mul_f32 v[114:115], v[114:115], v[116:117]
	v_lshlrev_b64 v[116:117], 1, v[142:143]
	v_cvt_pk_f16_f32 v121, v114, v115
	ds_bpermute_b32 v118, v152, v118
	ds_bpermute_b32 v119, v152, v119
	ds_bpermute_b32 v120, v152, v120
	ds_bpermute_b32 v121, v152, v121
	v_mov_b64_e32 v[114:115], s[92:93]
	v_mad_u32_u24 v122, v140, s3, v116
	s_waitcnt lgkmcnt(0)
	global_store_dwordx4 v122, v[118:121], s[92:93]
	v_mul_f32_e32 v122, 0xbfb8aa3b, v106
	v_mul_f32_e32 v123, 0xbfb8aa3b, v107
	v_mul_f32_e32 v118, 0xbfb8aa3b, v110
	v_mul_f32_e32 v119, 0xbfb8aa3b, v111
	v_exp_f32_e32 v118, v118
	v_exp_f32_e32 v119, v119
	v_mul_f32_e32 v120, 0xbfb8aa3b, v112
	v_mul_f32_e32 v121, 0xbfb8aa3b, v113
	v_exp_f32_e32 v120, v120
	v_exp_f32_e32 v121, v121
	v_exp_f32_e32 v122, v122
	v_exp_f32_e32 v123, v123
	v_mul_f32_e32 v124, 0xbfb8aa3b, v108
	v_mul_f32_e32 v125, 0xbfb8aa3b, v109
	v_add_f32_e32 v118, 1.0, v118
	v_add_f32_e32 v119, 1.0, v119
	v_exp_f32_e32 v124, v124
	v_exp_f32_e32 v125, v125
	v_rcp_f32_e32 v118, v118
	v_rcp_f32_e32 v119, v119
	v_add_f32_e32 v120, 1.0, v120
	v_add_f32_e32 v121, 1.0, v121
	v_rcp_f32_e32 v120, v120
	v_rcp_f32_e32 v121, v121
	v_add_f32_e32 v122, 1.0, v122
	v_add_f32_e32 v123, 1.0, v123
	v_rcp_f32_e32 v122, v122
	v_rcp_f32_e32 v123, v123
	v_add_f32_e32 v124, 1.0, v124
	v_add_f32_e32 v125, 1.0, v125
	v_pk_mul_f32 v[110:111], v[110:111], v[118:119]
	v_rcp_f32_e32 v124, v124
	v_rcp_f32_e32 v125, v125
	v_pk_mul_f32 v[102:103], v[110:111], v[102:103]
	v_pk_mul_f32 v[110:111], v[112:113], v[120:121]
	v_cvt_pk_f16_f32 v102, v102, v103
	v_pk_mul_f32 v[104:105], v[110:111], v[104:105]
	s_and_b64 vcc, exec, s[0:1]
	v_cvt_pk_f16_f32 v103, v104, v105
	v_pk_mul_f32 v[104:105], v[106:107], v[122:123]
	s_mov_b32 s36, s35
	v_pk_mul_f32 v[98:99], v[104:105], v[98:99]
	s_mov_b32 s8, s2
	v_cvt_pk_f16_f32 v104, v98, v99
	v_pk_mul_f32 v[98:99], v[108:109], v[124:125]
	s_mov_b64 s[16:17], s[6:7]
	v_pk_mul_f32 v[98:99], v[98:99], v[100:101]
	v_mul_f32_e32 v100, 0xbfb8aa3b, v96
	v_cvt_pk_f16_f32 v105, v98, v99
	ds_bpermute_b32 v102, v152, v102
	ds_bpermute_b32 v103, v152, v103
	ds_bpermute_b32 v104, v152, v104
	ds_bpermute_b32 v105, v152, v105
	v_or_b32_e32 v98, 16, v140
	v_mad_u32_u24 v98, v98, s3, v116
	s_waitcnt lgkmcnt(0)
	global_store_dwordx4 v98, v[102:105], s[92:93]
	v_mul_f32_e32 v98, 0xbfb8aa3b, v94
	v_mul_f32_e32 v99, 0xbfb8aa3b, v95
	v_exp_f32_e32 v98, v98
	v_exp_f32_e32 v99, v99
	v_mul_f32_e32 v101, 0xbfb8aa3b, v97
	v_exp_f32_e32 v100, v100
	v_exp_f32_e32 v101, v101
	v_mul_f32_e32 v102, 0xbfb8aa3b, v90
	v_mul_f32_e32 v103, 0xbfb8aa3b, v91
	v_exp_f32_e32 v102, v102
	v_exp_f32_e32 v103, v103
	v_mul_f32_e32 v104, 0xbfb8aa3b, v92
	v_mul_f32_e32 v105, 0xbfb8aa3b, v93
	v_add_f32_e32 v98, 1.0, v98
	v_add_f32_e32 v99, 1.0, v99
	v_exp_f32_e32 v104, v104
	v_exp_f32_e32 v105, v105
	v_rcp_f32_e32 v98, v98
	v_rcp_f32_e32 v99, v99
	v_add_f32_e32 v100, 1.0, v100
	v_add_f32_e32 v101, 1.0, v101
	v_rcp_f32_e32 v100, v100
	v_rcp_f32_e32 v101, v101
	v_add_f32_e32 v102, 1.0, v102
	v_add_f32_e32 v103, 1.0, v103
	v_rcp_f32_e32 v102, v102
	v_rcp_f32_e32 v103, v103
	v_add_f32_e32 v104, 1.0, v104
	v_add_f32_e32 v105, 1.0, v105
	v_pk_mul_f32 v[94:95], v[94:95], v[98:99]
	v_rcp_f32_e32 v104, v104
	v_rcp_f32_e32 v105, v105
	v_pk_mul_f32 v[86:87], v[94:95], v[86:87]
	v_pk_mul_f32 v[94:95], v[96:97], v[100:101]
	v_cvt_pk_f16_f32 v86, v86, v87
	v_pk_mul_f32 v[88:89], v[94:95], v[88:89]
	s_mov_b64 s[14:15], s[4:5]
	v_cvt_pk_f16_f32 v87, v88, v89
	v_pk_mul_f32 v[88:89], v[90:91], v[102:103]
	s_nop 0
	v_pk_mul_f32 v[82:83], v[88:89], v[82:83]
	s_nop 0
	v_cvt_pk_f16_f32 v88, v82, v83
	v_pk_mul_f32 v[82:83], v[92:93], v[104:105]
	s_nop 0
	v_pk_mul_f32 v[82:83], v[82:83], v[84:85]
	v_mul_f32_e32 v84, 0xbfb8aa3b, v80
	v_cvt_pk_f16_f32 v89, v82, v83
	ds_bpermute_b32 v86, v152, v86
	ds_bpermute_b32 v87, v152, v87
	ds_bpermute_b32 v88, v152, v88
	ds_bpermute_b32 v89, v152, v89
	v_or_b32_e32 v82, 32, v140
	v_mad_u32_u24 v82, v82, s3, v116
	s_waitcnt lgkmcnt(0)
	global_store_dwordx4 v82, v[86:89], s[92:93]
	v_mul_f32_e32 v82, 0xbfb8aa3b, v78
	v_mul_f32_e32 v83, 0xbfb8aa3b, v79
	v_exp_f32_e32 v82, v82
	v_exp_f32_e32 v83, v83
	v_mul_f32_e32 v85, 0xbfb8aa3b, v81
	v_exp_f32_e32 v84, v84
	v_exp_f32_e32 v85, v85
	v_mul_f32_e32 v86, 0xbfb8aa3b, v74
	v_mul_f32_e32 v87, 0xbfb8aa3b, v75
	v_exp_f32_e32 v86, v86
	v_exp_f32_e32 v87, v87
	v_mul_f32_e32 v88, 0xbfb8aa3b, v76
	v_mul_f32_e32 v89, 0xbfb8aa3b, v77
	v_add_f32_e32 v82, 1.0, v82
	v_add_f32_e32 v83, 1.0, v83
	v_exp_f32_e32 v88, v88
	v_exp_f32_e32 v89, v89
	v_rcp_f32_e32 v82, v82
	v_rcp_f32_e32 v83, v83
	v_add_f32_e32 v84, 1.0, v84
	v_add_f32_e32 v85, 1.0, v85
	v_rcp_f32_e32 v84, v84
	v_rcp_f32_e32 v85, v85
	v_add_f32_e32 v86, 1.0, v86
	v_add_f32_e32 v87, 1.0, v87
	v_rcp_f32_e32 v86, v86
	v_rcp_f32_e32 v87, v87
	v_add_f32_e32 v88, 1.0, v88
	v_add_f32_e32 v89, 1.0, v89
	v_pk_mul_f32 v[78:79], v[78:79], v[82:83]
	v_rcp_f32_e32 v88, v88
	v_rcp_f32_e32 v89, v89
	v_pk_mul_f32 v[70:71], v[78:79], v[70:71]
	v_pk_mul_f32 v[78:79], v[80:81], v[84:85]
	v_cvt_pk_f16_f32 v70, v70, v71
	v_pk_mul_f32 v[72:73], v[78:79], v[72:73]
	s_nop 0
	v_cvt_pk_f16_f32 v71, v72, v73
	v_pk_mul_f32 v[72:73], v[74:75], v[86:87]
	v_add_u32_e32 v74, 0x80, v140
	v_pk_mul_f32 v[66:67], v[72:73], v[66:67]
	s_nop 0
	v_cvt_pk_f16_f32 v72, v66, v67
	v_pk_mul_f32 v[66:67], v[76:77], v[88:89]
	s_nop 0
	v_pk_mul_f32 v[66:67], v[66:67], v[68:69]
	v_mul_f32_e32 v68, 0xbfb8aa3b, v64
	v_cvt_pk_f16_f32 v73, v66, v67
	ds_bpermute_b32 v70, v152, v70
	ds_bpermute_b32 v71, v152, v71
	ds_bpermute_b32 v72, v152, v72
	ds_bpermute_b32 v73, v152, v73
	v_or_b32_e32 v66, 48, v140
	v_mad_u32_u24 v66, v66, s3, v116
	s_waitcnt lgkmcnt(0)
	global_store_dwordx4 v66, v[70:73], s[92:93]
	v_mul_f32_e32 v66, 0xbfb8aa3b, v62
	v_mul_f32_e32 v67, 0xbfb8aa3b, v63
	v_exp_f32_e32 v66, v66
	v_exp_f32_e32 v67, v67
	v_mul_f32_e32 v69, 0xbfb8aa3b, v65
	v_exp_f32_e32 v68, v68
	v_exp_f32_e32 v69, v69
	v_mul_f32_e32 v70, 0xbfb8aa3b, v58
	v_mul_f32_e32 v71, 0xbfb8aa3b, v59
	v_exp_f32_e32 v70, v70
	v_exp_f32_e32 v71, v71
	v_mul_f32_e32 v72, 0xbfb8aa3b, v60
	v_mul_f32_e32 v73, 0xbfb8aa3b, v61
	v_add_f32_e32 v66, 1.0, v66
	v_add_f32_e32 v67, 1.0, v67
	v_exp_f32_e32 v72, v72
	v_exp_f32_e32 v73, v73
	v_rcp_f32_e32 v66, v66
	v_rcp_f32_e32 v67, v67
	v_add_f32_e32 v68, 1.0, v68
	v_add_f32_e32 v69, 1.0, v69
	v_rcp_f32_e32 v68, v68
	v_rcp_f32_e32 v69, v69
	v_add_f32_e32 v70, 1.0, v70
	v_add_f32_e32 v71, 1.0, v71
	v_rcp_f32_e32 v70, v70
	v_rcp_f32_e32 v71, v71
	v_add_f32_e32 v72, 1.0, v72
	v_add_f32_e32 v73, 1.0, v73
	v_pk_mul_f32 v[62:63], v[62:63], v[66:67]
	v_rcp_f32_e32 v72, v72
	v_rcp_f32_e32 v73, v73
	v_pk_mul_f32 v[54:55], v[62:63], v[54:55]
	v_pk_mul_f32 v[62:63], v[64:65], v[68:69]
	v_cvt_pk_f16_f32 v54, v54, v55
	v_pk_mul_f32 v[56:57], v[62:63], v[56:57]
	s_nop 0
	v_cvt_pk_f16_f32 v55, v56, v57
	v_pk_mul_f32 v[56:57], v[58:59], v[70:71]
	s_nop 0
	v_pk_mul_f32 v[50:51], v[56:57], v[50:51]
	s_nop 0
	v_cvt_pk_f16_f32 v56, v50, v51
	v_pk_mul_f32 v[50:51], v[60:61], v[72:73]
	s_nop 0
	v_pk_mul_f32 v[50:51], v[50:51], v[52:53]
	v_mul_f32_e32 v52, 0xbfb8aa3b, v48
	v_cvt_pk_f16_f32 v57, v50, v51
	ds_bpermute_b32 v54, v152, v54
	ds_bpermute_b32 v55, v152, v55
	ds_bpermute_b32 v56, v152, v56
	ds_bpermute_b32 v57, v152, v57
	v_mad_u32_u24 v50, v74, s3, v116
	s_waitcnt lgkmcnt(0)
	global_store_dwordx4 v50, v[54:57], s[92:93]
	v_mul_f32_e32 v50, 0xbfb8aa3b, v46
	v_mul_f32_e32 v51, 0xbfb8aa3b, v47
	v_exp_f32_e32 v50, v50
	v_exp_f32_e32 v51, v51
	v_mul_f32_e32 v53, 0xbfb8aa3b, v49
	v_exp_f32_e32 v52, v52
	v_exp_f32_e32 v53, v53
	v_mul_f32_e32 v54, 0xbfb8aa3b, v42
	v_mul_f32_e32 v55, 0xbfb8aa3b, v43
	v_exp_f32_e32 v54, v54
	v_exp_f32_e32 v55, v55
	v_mul_f32_e32 v56, 0xbfb8aa3b, v44
	v_mul_f32_e32 v57, 0xbfb8aa3b, v45
	v_add_f32_e32 v50, 1.0, v50
	v_add_f32_e32 v51, 1.0, v51
	v_exp_f32_e32 v56, v56
	v_exp_f32_e32 v57, v57
	v_rcp_f32_e32 v50, v50
	v_rcp_f32_e32 v51, v51
	v_add_f32_e32 v52, 1.0, v52
	v_add_f32_e32 v53, 1.0, v53
	v_rcp_f32_e32 v52, v52
	v_rcp_f32_e32 v53, v53
	v_add_f32_e32 v54, 1.0, v54
	v_add_f32_e32 v55, 1.0, v55
	v_rcp_f32_e32 v54, v54
	v_rcp_f32_e32 v55, v55
	v_add_f32_e32 v56, 1.0, v56
	v_add_f32_e32 v57, 1.0, v57
	v_pk_mul_f32 v[46:47], v[46:47], v[50:51]
	v_rcp_f32_e32 v56, v56
	v_rcp_f32_e32 v57, v57
	v_pk_mul_f32 v[38:39], v[46:47], v[38:39]
	v_pk_mul_f32 v[46:47], v[48:49], v[52:53]
	v_cvt_pk_f16_f32 v38, v38, v39
	v_pk_mul_f32 v[40:41], v[46:47], v[40:41]
	s_nop 0
	v_cvt_pk_f16_f32 v39, v40, v41
	v_pk_mul_f32 v[40:41], v[42:43], v[54:55]
	s_nop 0
	v_pk_mul_f32 v[34:35], v[40:41], v[34:35]
	s_nop 0
	v_cvt_pk_f16_f32 v40, v34, v35
	v_pk_mul_f32 v[34:35], v[44:45], v[56:57]
	s_nop 0
	v_pk_mul_f32 v[34:35], v[34:35], v[36:37]
	v_mul_f32_e32 v36, 0xbfb8aa3b, v30
	v_cvt_pk_f16_f32 v41, v34, v35
	ds_bpermute_b32 v38, v152, v38
	ds_bpermute_b32 v39, v152, v39
	ds_bpermute_b32 v40, v152, v40
	ds_bpermute_b32 v41, v152, v41
	v_add_u32_e32 v34, 0x90, v140
	v_mad_u32_u24 v34, v34, s3, v116
	s_waitcnt lgkmcnt(0)
	global_store_dwordx4 v34, v[38:41], s[92:93]
	v_mul_f32_e32 v34, 0xbfb8aa3b, v28
	v_mul_f32_e32 v35, 0xbfb8aa3b, v29
	v_exp_f32_e32 v34, v34
	v_exp_f32_e32 v35, v35
	v_mul_f32_e32 v37, 0xbfb8aa3b, v31
	v_exp_f32_e32 v36, v36
	v_exp_f32_e32 v37, v37
	v_mul_f32_e32 v38, 0xbfb8aa3b, v24
	v_mul_f32_e32 v39, 0xbfb8aa3b, v25
	v_exp_f32_e32 v38, v38
	v_exp_f32_e32 v39, v39
	v_mul_f32_e32 v40, 0xbfb8aa3b, v26
	v_mul_f32_e32 v41, 0xbfb8aa3b, v27
	v_add_f32_e32 v34, 1.0, v34
	v_add_f32_e32 v35, 1.0, v35
	v_exp_f32_e32 v40, v40
	v_exp_f32_e32 v41, v41
	v_rcp_f32_e32 v34, v34
	v_rcp_f32_e32 v35, v35
	v_add_f32_e32 v36, 1.0, v36
	v_add_f32_e32 v37, 1.0, v37
	v_rcp_f32_e32 v36, v36
	v_rcp_f32_e32 v37, v37
	v_add_f32_e32 v38, 1.0, v38
	v_add_f32_e32 v39, 1.0, v39
	v_rcp_f32_e32 v38, v38
	v_rcp_f32_e32 v39, v39
	v_add_f32_e32 v40, 1.0, v40
	v_add_f32_e32 v41, 1.0, v41
	v_pk_mul_f32 v[28:29], v[28:29], v[34:35]
	v_rcp_f32_e32 v40, v40
	v_rcp_f32_e32 v41, v41
	v_pk_mul_f32 v[20:21], v[28:29], v[20:21]
	v_pk_mul_f32 v[28:29], v[30:31], v[36:37]
	v_cvt_pk_f16_f32 v20, v20, v21
	v_pk_mul_f32 v[22:23], v[28:29], v[22:23]
	s_nop 0
	v_cvt_pk_f16_f32 v21, v22, v23
	v_pk_mul_f32 v[22:23], v[24:25], v[38:39]
	s_nop 0
	v_pk_mul_f32 v[16:17], v[22:23], v[16:17]
	s_nop 0
	v_cvt_pk_f16_f32 v22, v16, v17
	v_pk_mul_f32 v[16:17], v[26:27], v[40:41]
	s_nop 0
	v_pk_mul_f32 v[16:17], v[16:17], v[18:19]
	v_mul_f32_e32 v18, 0xbfb8aa3b, v14
	v_cvt_pk_f16_f32 v23, v16, v17
	ds_bpermute_b32 v20, v152, v20
	ds_bpermute_b32 v21, v152, v21
	ds_bpermute_b32 v22, v152, v22
	ds_bpermute_b32 v23, v152, v23
	v_add_u32_e32 v16, 0xa0, v140
	v_mad_u32_u24 v16, v16, s3, v116
	s_waitcnt lgkmcnt(0)
	global_store_dwordx4 v16, v[20:23], s[92:93]
	v_mul_f32_e32 v16, 0xbfb8aa3b, v12
	v_mul_f32_e32 v17, 0xbfb8aa3b, v13
	v_exp_f32_e32 v16, v16
	v_exp_f32_e32 v17, v17
	v_mul_f32_e32 v19, 0xbfb8aa3b, v15
	v_exp_f32_e32 v18, v18
	v_exp_f32_e32 v19, v19
	v_mul_f32_e32 v20, 0xbfb8aa3b, v8
	v_mul_f32_e32 v21, 0xbfb8aa3b, v9
	v_exp_f32_e32 v20, v20
	v_exp_f32_e32 v21, v21
	v_mul_f32_e32 v22, 0xbfb8aa3b, v10
	v_mul_f32_e32 v23, 0xbfb8aa3b, v11
	v_add_f32_e32 v16, 1.0, v16
	v_add_f32_e32 v17, 1.0, v17
	v_exp_f32_e32 v22, v22
	v_exp_f32_e32 v23, v23
	v_rcp_f32_e32 v16, v16
	v_rcp_f32_e32 v17, v17
	v_add_f32_e32 v18, 1.0, v18
	v_add_f32_e32 v19, 1.0, v19
	v_rcp_f32_e32 v18, v18
	v_rcp_f32_e32 v19, v19
	v_add_f32_e32 v20, 1.0, v20
	v_add_f32_e32 v21, 1.0, v21
	v_rcp_f32_e32 v20, v20
	v_rcp_f32_e32 v21, v21
	v_add_f32_e32 v22, 1.0, v22
	v_add_f32_e32 v23, 1.0, v23
	v_pk_mul_f32 v[12:13], v[12:13], v[16:17]
	v_rcp_f32_e32 v22, v22
	v_rcp_f32_e32 v23, v23
	v_pk_mul_f32 v[4:5], v[12:13], v[4:5]
	v_pk_mul_f32 v[12:13], v[14:15], v[18:19]
	v_cvt_pk_f16_f32 v4, v4, v5
	v_pk_mul_f32 v[6:7], v[12:13], v[6:7]
	s_nop 0
	v_cvt_pk_f16_f32 v5, v6, v7
	v_pk_mul_f32 v[6:7], v[8:9], v[20:21]
	s_nop 0
	v_pk_mul_f32 v[0:1], v[6:7], v[0:1]
	s_nop 0
	v_cvt_pk_f16_f32 v6, v0, v1
	v_pk_mul_f32 v[0:1], v[10:11], v[22:23]
	s_nop 0
	v_pk_mul_f32 v[0:1], v[0:1], v[2:3]
	s_nop 0
	v_cvt_pk_f16_f32 v7, v0, v1
	ds_bpermute_b32 v4, v152, v4
	ds_bpermute_b32 v5, v152, v5
	ds_bpermute_b32 v6, v152, v6
	ds_bpermute_b32 v7, v152, v7
	v_add_u32_e32 v0, 0xb0, v140
	v_mad_u32_u24 v0, v0, s3, v116
	s_waitcnt lgkmcnt(0)
	global_store_dwordx4 v0, v[4:7], s[92:93]
	s_cmp_eq_u32 s50, 0
	s_cbranch_scc1 .Lepib_up_nb
	s_mov_b32 s50, 0
	s_barrier
